# serial load-wait chains removed: NSA unit epilogue, selected-branch scratch accumulate, prep-phase row loads (all loads issued up front, counted waits)
# speedup vs baseline: 1.0098x; 1.0098x over previous
; __device__ __forceinline__ float wave_sum(float v) {
; #pragma unroll
;     for (int o = 1; o < 64; o <<= 1) v += __shfl_xor(v, o);
;     return v;
; }
; __device__ __forceinline__ void prep_phase(const float* X, bf16_t* XB, float* SSP) {
;     ...
;     for (int m = gw; m < MTOK; m += NGW) {
;         const v4f* xr = (const v4f*)(X + (size_t)m * DM) + lane;
;         v2u* o = (v2u*)(XB + (size_t)m * DM) + lane;
;         float s = 0.f;
; #pragma unroll
;         for (int j = 0; j < 8; ++j) { const v4f v = xr[64 * j]; s += (v.x * v.x + v.y * v.y) + (v.z * v.z + v.w * v.w); v2u w; w.x = pkbf(v.x, v.y); w.y = pkbf(v.z, v.w); o[64 * j] = w; }
;         s = wave_sum(s);
;         if (lane < 8) SSP[(size_t)lane * MTOK + m] = (lane == 0) ? s : 0.f;
;     }
.LBB0_54:
	s_waitcnt lgkmcnt(0)
	global_load_dwordx4 v[16:19], v[6:7], off offset:-4096
	global_load_dwordx4 v[20:23], v[6:7], off offset:-3072
	global_load_dwordx4 v[24:27], v[6:7], off offset:-2048
	global_load_dwordx4 v[28:31], v[6:7], off offset:-1024
	global_load_dwordx4 v[32:35], v[6:7], off
	global_load_dwordx4 v[36:39], v[6:7], off offset:1024
	global_load_dwordx4 v[40:43], v[6:7], off offset:2048
	global_load_dwordx4 v[44:47], v[6:7], off offset:3072
	s_waitcnt vmcnt(7)
	v_cvt_pk_bf16_f32 v48, v16, v17
	v_cvt_pk_bf16_f32 v49, v18, v19
	global_store_dwordx2 v[8:9], v[48:49], off
	v_mul_f32_e32 v3, v17, v17
	v_mul_f32_e32 v17, v19, v19
	v_fmac_f32_e32 v3, v16, v16
	v_fmac_f32_e32 v17, v18, v18
	v_add_f32_e32 v3, v3, v17
	s_waitcnt vmcnt(7)
	v_cvt_pk_bf16_f32 v50, v20, v21
	v_cvt_pk_bf16_f32 v51, v22, v23
	global_store_dwordx2 v[8:9], v[50:51], off offset:512
	v_mul_f32_e32 v16, v21, v21
	v_mul_f32_e32 v17, v23, v23
	v_fmac_f32_e32 v16, v20, v20
	v_fmac_f32_e32 v17, v22, v22
	v_add_f32_e32 v16, v16, v17
	v_add_f32_e32 v3, v3, v16
	s_waitcnt vmcnt(7)
	v_cvt_pk_bf16_f32 v48, v24, v25
	v_cvt_pk_bf16_f32 v49, v26, v27
	global_store_dwordx2 v[8:9], v[48:49], off offset:1024
	v_mul_f32_e32 v16, v25, v25
	v_mul_f32_e32 v17, v27, v27
	v_fmac_f32_e32 v16, v24, v24
	v_fmac_f32_e32 v17, v26, v26
	v_add_f32_e32 v16, v16, v17
	v_add_f32_e32 v3, v3, v16
	s_waitcnt vmcnt(7)
	v_cvt_pk_bf16_f32 v50, v28, v29
	v_cvt_pk_bf16_f32 v51, v30, v31
	global_store_dwordx2 v[8:9], v[50:51], off offset:1536
	v_mul_f32_e32 v16, v29, v29
	v_mul_f32_e32 v17, v31, v31
	v_fmac_f32_e32 v16, v28, v28
	v_fmac_f32_e32 v17, v30, v30
	v_add_f32_e32 v16, v16, v17
	v_add_f32_e32 v3, v3, v16
	s_waitcnt vmcnt(7)
	v_cvt_pk_bf16_f32 v48, v32, v33
	v_cvt_pk_bf16_f32 v49, v34, v35
	global_store_dwordx2 v[8:9], v[48:49], off offset:2048
	v_mul_f32_e32 v16, v33, v33
	v_mul_f32_e32 v17, v35, v35
	v_fmac_f32_e32 v16, v32, v32
	v_fmac_f32_e32 v17, v34, v34
	v_add_f32_e32 v16, v16, v17
	v_add_f32_e32 v3, v3, v16
	s_waitcnt vmcnt(7)
	v_cvt_pk_bf16_f32 v50, v36, v37
	v_cvt_pk_bf16_f32 v51, v38, v39
	global_store_dwordx2 v[8:9], v[50:51], off offset:2560
	v_mul_f32_e32 v16, v37, v37
	v_mul_f32_e32 v17, v39, v39
	v_fmac_f32_e32 v16, v36, v36
	v_fmac_f32_e32 v17, v38, v38
	v_add_f32_e32 v16, v16, v17
	v_add_f32_e32 v3, v3, v16
	s_waitcnt vmcnt(7)
	v_cvt_pk_bf16_f32 v48, v40, v41
	v_cvt_pk_bf16_f32 v49, v42, v43
	global_store_dwordx2 v[8:9], v[48:49], off offset:3072
	v_mul_f32_e32 v16, v41, v41
	v_mul_f32_e32 v17, v43, v43
	v_fmac_f32_e32 v16, v40, v40
	v_fmac_f32_e32 v17, v42, v42
	v_add_f32_e32 v16, v16, v17
	v_add_f32_e32 v3, v3, v16
	s_waitcnt vmcnt(7)
	v_cvt_pk_bf16_f32 v50, v44, v45
	v_cvt_pk_bf16_f32 v51, v46, v47
	global_store_dwordx2 v[8:9], v[50:51], off offset:3584
	v_mul_f32_e32 v16, v45, v45
	v_mul_f32_e32 v17, v47, v47
	v_fmac_f32_e32 v16, v44, v44
	v_fmac_f32_e32 v17, v46, v46
	v_add_f32_e32 v16, v16, v17
	v_add_f32_e32 v3, v3, v16
	ds_bpermute_b32 v16, v1, v3
	s_waitcnt lgkmcnt(0)
	v_add_f32_e32 v3, v3, v16
	ds_bpermute_b32 v16, v11, v3
	s_waitcnt lgkmcnt(0)
	v_add_f32_e32 v3, v3, v16
	ds_bpermute_b32 v16, v12, v3
	s_waitcnt lgkmcnt(0)
	v_add_f32_e32 v3, v3, v16
	ds_bpermute_b32 v16, v13, v3
	s_waitcnt lgkmcnt(0)
	v_add_f32_e32 v3, v3, v16
	ds_bpermute_b32 v16, v14, v3
	s_waitcnt lgkmcnt(0)
	v_add_f32_e32 v3, v3, v16
	ds_bpermute_b32 v16, v15, v3
	s_and_saveexec_b64 s[4:5], vcc
	s_cbranch_execz .LBB0_53
	s_waitcnt lgkmcnt(0)
	v_add_f32_e32 v3, v3, v16
	v_cndmask_b32_e64 v3, 0, v3, s[0:1]
	global_store_dword v[4:5], v3, off
	s_branch .LBB0_53

; #define NSA_GATE(i) (1.f / (1.f + __expf(-bf2f(QKV[(size_t)(b * SEQ + qpos) * EVEN_PAD + E_GT + hq * 3 + (i)]))))
; __device__ __forceinline__ void store_o(bf16_t* Orow, const v16f (&o)[2], int hi) {
; #pragma unroll
;     for (int dt = 0; dt < 2; ++dt)
; #pragma unroll
;         for (int g = 0; g < 4; ++g) { v2u w; w.x = pkbf(o[dt][4 * g], o[dt][4 * g + 1]); w.y = pkbf(o[dt][4 * g + 2], o[dt][4 * g + 3]);
;             *(v2u*)(Orow + dt * 32 + 8 * g + 4 * hi) = w; }
; }
; __device__ __forceinline__ void nsa_phase(LAS unsigned char* lds, const bf16_t* QKV, const float* relb, const bf16_t* KCMP, const bf16_t* VCMP, bf16_t* AO, float* SCRG, unsigned* CTR, const float* sinks) {
;     ...
;             l += __shfl_xor(l, 32);
;             const float scl = (l > 0.f) ? NSA_GATE(2) / l : 0.f;
; #pragma unroll
;             for (int r = 0; r < 16; ++r) { oT[0][r] = SCR[r * 512 + tid] + oT[0][r] * scl; oT[1][r] = SCR[(16 + r) * 512 + tid] + oT[1][r] * scl; }
;             store_o(AO + (size_t)(b * SEQ + qpos) * DM + 1024 + hq * 64, oT, hi);
.LBB0_468:
	s_or_b64 exec, exec, s[0:1]
	v_lshlrev_b32_e32 v48, 2, v186
	global_load_dword v64, v48, s[20:21]
	global_load_dword v65, v48, s[20:21] offset:2048
	v_add_u32_e32 v48, 0x1000, v48
	global_load_dword v66, v48, s[20:21]
	global_load_dword v67, v48, s[20:21] offset:2048
	v_add_u32_e32 v48, 0x1000, v48
	global_load_dword v68, v48, s[20:21]
	global_load_dword v69, v48, s[20:21] offset:2048
	v_add_u32_e32 v48, 0x1000, v48
	global_load_dword v70, v48, s[20:21]
	global_load_dword v71, v48, s[20:21] offset:2048
	v_add_u32_e32 v48, 0x1000, v48
	global_load_dword v72, v48, s[20:21]
	global_load_dword v73, v48, s[20:21] offset:2048
	v_add_u32_e32 v48, 0x1000, v48
	global_load_dword v74, v48, s[20:21]
	global_load_dword v75, v48, s[20:21] offset:2048
	v_add_u32_e32 v48, 0x1000, v48
	global_load_dword v76, v48, s[20:21]
	global_load_dword v77, v48, s[20:21] offset:2048
	v_add_u32_e32 v48, 0x1000, v48
	global_load_dword v78, v48, s[20:21]
	global_load_dword v79, v48, s[20:21] offset:2048
	v_add_u32_e32 v48, 0x1000, v48
	global_load_dword v80, v48, s[20:21]
	global_load_dword v81, v48, s[20:21] offset:2048
	v_add_u32_e32 v48, 0x1000, v48
	global_load_dword v82, v48, s[20:21]
	global_load_dword v83, v48, s[20:21] offset:2048
	v_add_u32_e32 v48, 0x1000, v48
	global_load_dword v84, v48, s[20:21]
	global_load_dword v85, v48, s[20:21] offset:2048
	v_add_u32_e32 v48, 0x1000, v48
	global_load_dword v86, v48, s[20:21]
	global_load_dword v87, v48, s[20:21] offset:2048
	v_add_u32_e32 v48, 0x1000, v48
	global_load_dword v88, v48, s[20:21]
	global_load_dword v89, v48, s[20:21] offset:2048
	v_add_u32_e32 v48, 0x1000, v48
	global_load_dword v90, v48, s[20:21]
	global_load_dword v91, v48, s[20:21] offset:2048
	v_add_u32_e32 v48, 0x1000, v48
	global_load_dword v92, v48, s[20:21]
	global_load_dword v93, v48, s[20:21] offset:2048
	v_add_u32_e32 v48, 0x1000, v48
	global_load_dword v94, v48, s[20:21]
	global_load_dword v95, v48, s[20:21] offset:2048
	s_mov_b64 s[0:1], 0
	s_waitcnt vmcnt(30)
	v_pk_fma_f32 v[2:3], v[2:3], v[34:35], v[64:65] op_sel_hi:[1,0,1]
	s_waitcnt vmcnt(28)
	v_pk_fma_f32 v[4:5], v[4:5], v[34:35], v[66:67] op_sel_hi:[1,0,1]
	s_waitcnt vmcnt(26)
	v_pk_fma_f32 v[6:7], v[6:7], v[34:35], v[68:69] op_sel_hi:[1,0,1]
	s_waitcnt vmcnt(24)
	v_pk_fma_f32 v[8:9], v[8:9], v[34:35], v[70:71] op_sel_hi:[1,0,1]
	s_waitcnt vmcnt(22)
	v_pk_fma_f32 v[10:11], v[10:11], v[34:35], v[72:73] op_sel_hi:[1,0,1]
	s_waitcnt vmcnt(20)
	v_pk_fma_f32 v[12:13], v[12:13], v[34:35], v[74:75] op_sel_hi:[1,0,1]
	s_waitcnt vmcnt(18)
	v_pk_fma_f32 v[14:15], v[14:15], v[34:35], v[76:77] op_sel_hi:[1,0,1]
	s_waitcnt vmcnt(16)
	v_pk_fma_f32 v[16:17], v[16:17], v[34:35], v[78:79] op_sel_hi:[1,0,1]
	s_waitcnt vmcnt(14)
	v_pk_fma_f32 v[18:19], v[18:19], v[34:35], v[80:81] op_sel_hi:[1,0,1]
	s_waitcnt vmcnt(12)
	v_pk_fma_f32 v[20:21], v[20:21], v[34:35], v[82:83] op_sel_hi:[1,0,1]
	s_waitcnt vmcnt(10)
	v_pk_fma_f32 v[22:23], v[22:23], v[34:35], v[84:85] op_sel_hi:[1,0,1]
	s_waitcnt vmcnt(8)
	v_pk_fma_f32 v[24:25], v[24:25], v[34:35], v[86:87] op_sel_hi:[1,0,1]
	s_waitcnt vmcnt(6)
	v_pk_fma_f32 v[26:27], v[26:27], v[34:35], v[88:89] op_sel_hi:[1,0,1]
	s_waitcnt vmcnt(4)
	v_pk_fma_f32 v[28:29], v[28:29], v[34:35], v[90:91] op_sel_hi:[1,0,1]
	s_waitcnt vmcnt(2)
	v_pk_fma_f32 v[30:31], v[30:31], v[34:35], v[92:93] op_sel_hi:[1,0,1]
	s_waitcnt vmcnt(0)
	v_pk_fma_f32 v[32:33], v[32:33], v[34:35], v[94:95] op_sel_hi:[1,0,1]
	v_cvt_pk_bf16_f32 v2, v2, v3
	v_cvt_pk_bf16_f32 v3, v4, v5
	v_lshlrev_b64 v[34:35], 12, v[0:1]
	v_lshl_add_u64 v[34:35], s[10:11], 0, v[34:35]
	v_lshl_add_u64 v[34:35], s[16:17], 1, v[34:35]
	v_lshlrev_b32_e32 v0, 3, v192
	v_lshl_add_u64 v[34:35], v[34:35], 0, v[0:1]
	global_store_dwordx2 v[34:35], v[2:3], off offset:2048
	v_cvt_pk_bf16_f32 v2, v6, v7
	v_cvt_pk_bf16_f32 v3, v8, v9
	global_store_dwordx2 v[34:35], v[2:3], off offset:2064
	v_cvt_pk_bf16_f32 v2, v10, v11
	v_cvt_pk_bf16_f32 v3, v12, v13
	global_store_dwordx2 v[34:35], v[2:3], off offset:2080
	v_cvt_pk_bf16_f32 v2, v14, v15
	v_cvt_pk_bf16_f32 v3, v16, v17
	global_store_dwordx2 v[34:35], v[2:3], off offset:2096
	v_cvt_pk_bf16_f32 v2, v18, v19
	v_cvt_pk_bf16_f32 v3, v20, v21
	global_store_dwordx2 v[34:35], v[2:3], off offset:2112
	v_cvt_pk_bf16_f32 v2, v22, v23
	v_cvt_pk_bf16_f32 v3, v24, v25
	global_store_dwordx2 v[34:35], v[2:3], off offset:2128
	v_cvt_pk_bf16_f32 v2, v26, v27
	v_cvt_pk_bf16_f32 v3, v28, v29
	global_store_dwordx2 v[34:35], v[2:3], off offset:2144
	v_cvt_pk_bf16_f32 v2, v30, v31
	v_cvt_pk_bf16_f32 v3, v32, v33
	global_store_dwordx2 v[34:35], v[2:3], off offset:2160

; #define NSA_GATE(i) (1.f / (1.f + __expf(-bf2f(QKV[(size_t)(b * SEQ + qpos) * EVEN_PAD + E_GT + hq * 3 + (i)]))))
; __device__ __forceinline__ void nsa_phase(LAS unsigned char* lds, const bf16_t* QKV, const float* relb, const bf16_t* KCMP, const bf16_t* VCMP, bf16_t* AO, float* SCRG, unsigned* CTR, const float* sinks) {
;     ...
;             l += __shfl_xor(l, 32);
;             const float scl = (l > 0.f) ? NSA_GATE(1) / l : 0.f;
; #pragma unroll
;             for (int r = 0; r < 16; ++r) { SCR[r * 512 + tid] += oT[0][r] * scl; SCR[(16 + r) * 512 + tid] += oT[1][r] * scl; }
;     ...
;             attn_engine<false>(lds, Kg, Vg, EVEN_PAD, nullptr, RangeSeq{(q0 >= 511) ? ((q0 - 511) >> 6) : 0, (q0 + 31) >> 6}, qf, oT, m, l, sc, tid, lane);
.LBB0_562:
	s_or_b64 exec, exec, s[0:1]
	v_lshlrev_b32_e32 v48, 2, v186
	v_lshlrev_b32_e32 v49, 2, v186
	global_load_dword v64, v48, s[20:21]
	global_load_dword v65, v48, s[20:21] offset:2048
	v_add_u32_e32 v48, 0x1000, v48
	global_load_dword v66, v48, s[20:21]
	global_load_dword v67, v48, s[20:21] offset:2048
	v_add_u32_e32 v48, 0x1000, v48
	global_load_dword v68, v48, s[20:21]
	global_load_dword v69, v48, s[20:21] offset:2048
	v_add_u32_e32 v48, 0x1000, v48
	global_load_dword v70, v48, s[20:21]
	global_load_dword v71, v48, s[20:21] offset:2048
	v_add_u32_e32 v48, 0x1000, v48
	global_load_dword v72, v48, s[20:21]
	global_load_dword v73, v48, s[20:21] offset:2048
	v_add_u32_e32 v48, 0x1000, v48
	global_load_dword v74, v48, s[20:21]
	global_load_dword v75, v48, s[20:21] offset:2048
	v_add_u32_e32 v48, 0x1000, v48
	global_load_dword v76, v48, s[20:21]
	global_load_dword v77, v48, s[20:21] offset:2048
	v_add_u32_e32 v48, 0x1000, v48
	global_load_dword v78, v48, s[20:21]
	global_load_dword v79, v48, s[20:21] offset:2048
	v_add_u32_e32 v48, 0x1000, v48
	global_load_dword v80, v48, s[20:21]
	global_load_dword v81, v48, s[20:21] offset:2048
	v_add_u32_e32 v48, 0x1000, v48
	global_load_dword v82, v48, s[20:21]
	global_load_dword v83, v48, s[20:21] offset:2048
	v_add_u32_e32 v48, 0x1000, v48
	global_load_dword v84, v48, s[20:21]
	global_load_dword v85, v48, s[20:21] offset:2048
	v_add_u32_e32 v48, 0x1000, v48
	global_load_dword v86, v48, s[20:21]
	global_load_dword v87, v48, s[20:21] offset:2048
	v_add_u32_e32 v48, 0x1000, v48
	global_load_dword v88, v48, s[20:21]
	global_load_dword v89, v48, s[20:21] offset:2048
	v_add_u32_e32 v48, 0x1000, v48
	global_load_dword v90, v48, s[20:21]
	global_load_dword v91, v48, s[20:21] offset:2048
	v_add_u32_e32 v48, 0x1000, v48
	global_load_dword v92, v48, s[20:21]
	global_load_dword v93, v48, s[20:21] offset:2048
	v_add_u32_e32 v48, 0x1000, v48
	global_load_dword v94, v48, s[20:21]
	global_load_dword v95, v48, s[20:21] offset:2048
	v_mov_b32_e32 v186, v202
	s_waitcnt vmcnt(30)
	v_fmac_f32_e32 v64, v2, v0
	v_fmac_f32_e32 v65, v3, v0
	global_store_dword v49, v64, s[20:21]
	global_store_dword v49, v65, s[20:21] offset:2048
	v_add_u32_e32 v49, 0x1000, v49
	s_waitcnt vmcnt(30)
	v_fmac_f32_e32 v66, v4, v0
	v_fmac_f32_e32 v67, v5, v0
	global_store_dword v49, v66, s[20:21]
	global_store_dword v49, v67, s[20:21] offset:2048
	v_add_u32_e32 v49, 0x1000, v49
	s_waitcnt vmcnt(30)
	v_fmac_f32_e32 v68, v6, v0
	v_fmac_f32_e32 v69, v7, v0
	global_store_dword v49, v68, s[20:21]
	global_store_dword v49, v69, s[20:21] offset:2048
	v_add_u32_e32 v49, 0x1000, v49
	s_waitcnt vmcnt(30)
	v_fmac_f32_e32 v70, v8, v0
	v_fmac_f32_e32 v71, v9, v0
	global_store_dword v49, v70, s[20:21]
	global_store_dword v49, v71, s[20:21] offset:2048
	v_add_u32_e32 v49, 0x1000, v49
	s_waitcnt vmcnt(30)
	v_fmac_f32_e32 v72, v10, v0
	v_fmac_f32_e32 v73, v11, v0
	global_store_dword v49, v72, s[20:21]
	global_store_dword v49, v73, s[20:21] offset:2048
	v_add_u32_e32 v49, 0x1000, v49
	s_waitcnt vmcnt(30)
	v_fmac_f32_e32 v74, v12, v0
	v_fmac_f32_e32 v75, v13, v0
	global_store_dword v49, v74, s[20:21]
	global_store_dword v49, v75, s[20:21] offset:2048
	v_add_u32_e32 v49, 0x1000, v49
	s_waitcnt vmcnt(30)
	v_fmac_f32_e32 v76, v14, v0
	v_fmac_f32_e32 v77, v15, v0
	global_store_dword v49, v76, s[20:21]
	global_store_dword v49, v77, s[20:21] offset:2048
	v_add_u32_e32 v49, 0x1000, v49
	s_waitcnt vmcnt(30)
	v_fmac_f32_e32 v78, v16, v0
	v_fmac_f32_e32 v79, v17, v0
	global_store_dword v49, v78, s[20:21]
	global_store_dword v49, v79, s[20:21] offset:2048
	v_add_u32_e32 v49, 0x1000, v49
	s_waitcnt vmcnt(30)
	v_fmac_f32_e32 v80, v18, v0
	v_fmac_f32_e32 v81, v19, v0
	global_store_dword v49, v80, s[20:21]
	global_store_dword v49, v81, s[20:21] offset:2048
	v_add_u32_e32 v49, 0x1000, v49
	s_waitcnt vmcnt(30)
	v_fmac_f32_e32 v82, v20, v0
	v_fmac_f32_e32 v83, v21, v0
	global_store_dword v49, v82, s[20:21]
	global_store_dword v49, v83, s[20:21] offset:2048
	v_add_u32_e32 v49, 0x1000, v49
	s_waitcnt vmcnt(30)
	v_fmac_f32_e32 v84, v22, v0
	v_fmac_f32_e32 v85, v23, v0
	global_store_dword v49, v84, s[20:21]
	global_store_dword v49, v85, s[20:21] offset:2048
	v_add_u32_e32 v49, 0x1000, v49
	s_waitcnt vmcnt(30)
	v_fmac_f32_e32 v86, v24, v0
	v_fmac_f32_e32 v87, v25, v0
	global_store_dword v49, v86, s[20:21]
	global_store_dword v49, v87, s[20:21] offset:2048
	v_add_u32_e32 v49, 0x1000, v49
	s_waitcnt vmcnt(30)
	v_fmac_f32_e32 v88, v26, v0
	v_fmac_f32_e32 v89, v27, v0
	global_store_dword v49, v88, s[20:21]
	global_store_dword v49, v89, s[20:21] offset:2048
	v_add_u32_e32 v49, 0x1000, v49
	s_waitcnt vmcnt(30)
	v_fmac_f32_e32 v90, v28, v0
	v_fmac_f32_e32 v91, v29, v0
	global_store_dword v49, v90, s[20:21]
	global_store_dword v49, v91, s[20:21] offset:2048
	v_add_u32_e32 v49, 0x1000, v49
	s_waitcnt vmcnt(30)
	v_fmac_f32_e32 v92, v30, v0
	v_fmac_f32_e32 v93, v31, v0
	global_store_dword v49, v92, s[20:21]
	global_store_dword v49, v93, s[20:21] offset:2048
	v_add_u32_e32 v49, 0x1000, v49
	s_waitcnt vmcnt(30)
	v_fmac_f32_e32 v94, v32, v0
	v_fmac_f32_e32 v95, v33, v0
	global_store_dword v49, v94, s[20:21]
	global_store_dword v49, v95, s[20:21] offset:2048
	s_add_i32 s0, s45, 0xfffffe01
	s_ashr_i32 s0, s0, 6
	s_cmpk_lt_i32 s44, 0x70
	s_cselect_b32 s27, s0, 0
	s_lshr_b32 s26, s45, 6
	s_cmp_le_i32 s27, s26
	s_cselect_b64 s[22:23], -1, 0
	s_and_b64 s[0:1], s[22:23], exec
	s_nop 0
	v_and_b32_e32 v10, 31, v186
	v_or_b32_e32 v187, s45, v10
	s_cselect_b32 s45, s27, -1
	v_bfe_u32 v192, v186, 5, 1
	s_cmp_lt_i32 s45, 0
	s_cbranch_scc1 .LBB0_596
; #define LAS __attribute__((address_space(3)))
;     ...
;     int tc = seq.pop(); if (tc < 0) return;
;     int tn = seq.pop(), tnn = (tn >= 0) ? seq.pop() : -1;
;     LAS float* AUXL = (LAS float*)(lds + ATT_AUX);
;     v4u kr = ld_tile(Kg, 64 * tc, pitch, tid), vr = ld_tile(Vg, 64 * tc, pitch, tid); float ar = 0.f;
;     if (AUX && tid < 64) ar = auxg[64 * tc + tid];
;     v4u kr2 = kr, vr2 = vr; float ar2 = 0.f;
;     if (tn >= 0) { kr2 = ld_tile(Kg, 64 * tn, pitch, tid); vr2 = ld_tile(Vg, 64 * tn, pitch, tid); if (AUX && tid < 64) ar2 = auxg[64 * tn + tid]; }
; __device__ __forceinline__ void nsa_phase(LAS unsigned char* lds, const bf16_t* QKV, const float* relb, const bf16_t* KCMP, const bf16_t* VCMP, bf16_t* AO, float* SCRG, unsigned* CTR, const float* sinks) {
;     ...
;             const bf16_t* Kg = QKV + (size_t)(b * SEQ) * EVEN_PAD + E_KW + g * 64; const bf16_t* Vg = QKV + (size_t)(b * SEQ) * EVEN_PAD + E_VW + g * 64;
	s_lshl_b32 s0, s48, 1
	s_add_u32 s4, s46, s0
	s_addc_u32 s5, s47, 0
	s_add_u32 s0, s4, 0x1800
	s_addc_u32 s1, s5, 0
	s_add_u32 s4, s4, 0x1900
	s_addc_u32 s5, s5, 0
	v_ashrrev_i32_e32 v193, 3, v186
	v_lshlrev_b32_e32 v11, 3, v186
	v_lshl_add_u32 v6, s45, 6, v193
	v_and_b32_e32 v0, 56, v11
	v_mov_b64_e32 v[4:5], s[4:5]
	v_mov_b64_e32 v[2:3], s[0:1]
	v_lshlrev_b32_e32 v0, 1, v0
	v_mad_i64_i32 v[4:5], s[24:25], v6, s60, v[4:5]
	v_mad_i64_i32 v[2:3], s[24:25], v6, s60, v[2:3]
	v_lshl_add_u64 v[4:5], v[4:5], 0, v[0:1]
	v_lshl_add_u64 v[2:3], v[2:3], 0, v[0:1]
	global_load_dwordx4 v[150:153], v[4:5], off
	global_load_dwordx4 v[146:149], v[2:3], off
	v_cndmask_b32_e64 v2, 0, 1, s[22:23]
	s_waitcnt vmcnt(0)
	v_mov_b64_e32 v[6:7], v[146:147]
	v_readfirstlane_b32 s22, v2
	s_add_i32 s27, s27, s22
	s_cmp_le_i32 s27, s26
	s_cselect_b64 s[24:25], -1, 0
	s_and_b64 s[22:23], s[24:25], exec
	s_cselect_b32 s44, s27, -1
	s_cmp_gt_i32 s44, -1
	v_mov_b64_e32 v[2:3], v[150:151]
	s_cselect_b64 s[22:23], -1, 0
	s_cmp_lt_i32 s44, 0
	v_mov_b64_e32 v[4:5], v[152:153]
	v_mov_b64_e32 v[8:9], v[148:149]
	s_cbranch_scc1 .LBB0_565
	v_lshl_add_u32 v6, s44, 6, v193
	v_mov_b64_e32 v[2:3], s[0:1]
	v_mov_b64_e32 v[4:5], s[4:5]
	v_mad_i64_i32 v[2:3], s[46:47], v6, s60, v[2:3]
	v_mad_i64_i32 v[4:5], s[46:47], v6, s60, v[4:5]
	v_lshl_add_u64 v[2:3], v[2:3], 0, v[0:1]
	v_lshl_add_u64 v[4:5], v[4:5], 0, v[0:1]
	global_load_dwordx4 v[6:9], v[2:3], off
	s_nop 0
	global_load_dwordx4 v[2:5], v[4:5], off
